# P5 lora_prep rewritten by hand: 11 rows in flight per wave (on top of thin-phase hoist)
# speedup vs baseline: 1.0038x; 1.0038x over previous
; __device__ __forceinline__ unsigned pk2(float lo, float hi) { const bfx2 b = __builtin_convertvector((f32x2){lo, hi}, bfx2); return __builtin_bit_cast(unsigned, b); }
; __device__ __forceinline__ float bf2f(bf16 v) { return __uint_as_float((unsigned)v << 16); }
; __device__ __forceinline__ float sigmoidf_(float x) { return __builtin_amdgcn_rcpf(1.0f + __builtin_amdgcn_exp2f(-1.4426950408889634f * x)); }
; __device__ __forceinline__ float prw_prev(const P& p, const bf16* PRW, int m, int col) {
;     if (m < MP) { return (m & (TP - 1)) == 0 ? 0.f : bf2f(PRW[(size_t)(m - 1) * RWP + col]); }
;     const int x = m - MP; return (x & 3) == 0 ? p.in[I_SSH][(size_t)(x >> 2) * RWP + col] : bf2f(PRW[(size_t)(m - 1) * RWP + col]);
; }
; __device__ __forceinline__ void lora_prep(const P& p, Frame& F) {
;     const bf16* PRW = (const bf16*)(p.ws + WS_PRW); bf16* AL = (bf16*)(p.ws + WS_ALORA); const float* mu = p.in[I_MU];
;     const int gt = F.bid * NTHR + F.tid, NGT = F.G * NTHR;
;     for (int i = gt; i < MPAD * 256; i += NGT) { const int m = i >> 8, k = i & 255; float v = 0.f;
;         if (m < MT) { const int col = 3072 + k; const float pc = bf2f(PRW[(size_t)m * RWP + col]), pp = prw_prev(p, PRW, m, col); const float xs = pc + (pp - pc) * mu[col];
;             v = k < 64 ? 1.0f - 2.0f / (1.0f + __expf(2.0f * xs)) : (k < 128 ? xs : sigmoidf_(xs)); }
;         AL[i] = (bf16)(pk2(v, 0.f) & 0xffffu); }
.LBB0_1342:
	s_or_b64 exec, exec, s[0:1]
	v_mov_b32_e32 v3, v0
	s_waitcnt lgkmcnt(0)
	s_barrier
	s_mov_b32 s0, 0x410000
	v_add_u32_e32 v2, s74, v3
	v_cmp_gt_i32_e32 vcc, s0, v2
	s_and_saveexec_b64 s[4:5], vcc
	s_cbranch_execz .LBB0_1361
	v_and_b32_e32 v2, 0xff, v0
	v_add_u32_e32 v3, 0xc00, v2
	v_lshlrev_b32_e32 v4, 2, v3
	v_lshlrev_b32_e32 v3, 1, v3
	v_lshlrev_b32_e32 v2, 1, v2
	v_readlane_b32 s30, v253, 20
	v_readlane_b32 s31, v253, 21
	v_readfirstlane_b32 s11, v0
	v_readlane_b32 s0, v253, 4
	v_readlane_b32 s9, v253, 0
	v_readlane_b32 s2, v253, 46
	v_readlane_b32 s3, v253, 47
	s_nop 3
	global_load_dword v5, v4, s[30:31]
	s_lshl_b32 s0, s0, 1
	s_lshr_b32 s8, s11, 8
	s_add_i32 s8, s8, s0
	s_lshl_b32 s9, s9, 1
	s_bfe_u32 s11, s11, 0x20006
	s_add_u32 s14, s2, 0x3b870000
	s_addc_u32 s15, s3, 0
.Lp5_trip:
	s_mov_b32 s10, s8
	s_cmp_ge_u32 s10, 0x4080
	s_cbranch_scc1 .Lp5_iss_done
	s_mul_i32 s2, s10, 0x1a00
	s_add_u32 s2, s62, s2
	s_addc_u32 s3, s63, 0
	s_and_b32 s6, s10, 0x7ff
	global_load_ushort v16, v3, s[2:3]
	s_cmp_lt_u32 s10, 0x4000
	s_cbranch_scc0 .Lp5_is_s0
	s_cmp_eq_u32 s6, 0
	s_cbranch_scc1 .Lp5_is_e0
.Lp5_is_p0:
	s_sub_u32 s2, s2, 0x1a00
	s_subb_u32 s3, s3, 0
	s_nop 0
	global_load_ushort v27, v3, s[2:3]
	s_branch .Lp5_is_e0
.Lp5_is_s0:
	s_and_b32 s6, s10, 3
	s_cmp_lg_u32 s6, 0
	s_cbranch_scc1 .Lp5_is_p0
	s_sub_u32 s6, s10, 0x4000
	s_lshr_b32 s6, s6, 2
	s_mul_i32 s6, s6, 0x3400
	s_add_u32 s6, s70, s6
	s_addc_u32 s7, s71, 0
	s_nop 0
	global_load_dword v27, v4, s[6:7]
.Lp5_is_e0:
	s_add_i32 s10, s10, s9
	s_cmp_ge_u32 s10, 0x4080
	s_cbranch_scc1 .Lp5_iss_done
	s_mul_i32 s2, s10, 0x1a00
	s_add_u32 s2, s62, s2
	s_addc_u32 s3, s63, 0
	s_and_b32 s6, s10, 0x7ff
	global_load_ushort v17, v3, s[2:3]
	s_cmp_lt_u32 s10, 0x4000
	s_cbranch_scc0 .Lp5_is_s1
	s_cmp_eq_u32 s6, 0
	s_cbranch_scc1 .Lp5_is_e1
.Lp5_is_p1:
	s_sub_u32 s2, s2, 0x1a00
	s_subb_u32 s3, s3, 0
	s_nop 0
	global_load_ushort v28, v3, s[2:3]
	s_branch .Lp5_is_e1
.Lp5_is_s1:
	s_and_b32 s6, s10, 3
	s_cmp_lg_u32 s6, 0
	s_cbranch_scc1 .Lp5_is_p1
	s_sub_u32 s6, s10, 0x4000
	s_lshr_b32 s6, s6, 2
	s_mul_i32 s6, s6, 0x3400
	s_add_u32 s6, s70, s6
	s_addc_u32 s7, s71, 0
	s_nop 0
	global_load_dword v28, v4, s[6:7]
.Lp5_is_e1:
	s_add_i32 s10, s10, s9
	s_cmp_ge_u32 s10, 0x4080
	s_cbranch_scc1 .Lp5_iss_done
	s_mul_i32 s2, s10, 0x1a00
	s_add_u32 s2, s62, s2
	s_addc_u32 s3, s63, 0
	s_and_b32 s6, s10, 0x7ff
	global_load_ushort v18, v3, s[2:3]
	s_cmp_lt_u32 s10, 0x4000
	s_cbranch_scc0 .Lp5_is_s2
	s_cmp_eq_u32 s6, 0
	s_cbranch_scc1 .Lp5_is_e2
.Lp5_is_p2:
	s_sub_u32 s2, s2, 0x1a00
	s_subb_u32 s3, s3, 0
	s_nop 0
	global_load_ushort v29, v3, s[2:3]
	s_branch .Lp5_is_e2
.Lp5_is_s2:
	s_and_b32 s6, s10, 3
	s_cmp_lg_u32 s6, 0
	s_cbranch_scc1 .Lp5_is_p2
	s_sub_u32 s6, s10, 0x4000
	s_lshr_b32 s6, s6, 2
	s_mul_i32 s6, s6, 0x3400
	s_add_u32 s6, s70, s6
	s_addc_u32 s7, s71, 0
	s_nop 0
	global_load_dword v29, v4, s[6:7]
.Lp5_is_e2:
	s_add_i32 s10, s10, s9
	s_cmp_ge_u32 s10, 0x4080
	s_cbranch_scc1 .Lp5_iss_done
	s_mul_i32 s2, s10, 0x1a00
	s_add_u32 s2, s62, s2
	s_addc_u32 s3, s63, 0
	s_and_b32 s6, s10, 0x7ff
	global_load_ushort v19, v3, s[2:3]
	s_cmp_lt_u32 s10, 0x4000
	s_cbranch_scc0 .Lp5_is_s3
	s_cmp_eq_u32 s6, 0
	s_cbranch_scc1 .Lp5_is_e3
.Lp5_is_p3:
	s_sub_u32 s2, s2, 0x1a00
	s_subb_u32 s3, s3, 0
	s_nop 0
	global_load_ushort v30, v3, s[2:3]
	s_branch .Lp5_is_e3
.Lp5_is_s3:
	s_and_b32 s6, s10, 3
	s_cmp_lg_u32 s6, 0
	s_cbranch_scc1 .Lp5_is_p3
	s_sub_u32 s6, s10, 0x4000
	s_lshr_b32 s6, s6, 2
	s_mul_i32 s6, s6, 0x3400
	s_add_u32 s6, s70, s6
	s_addc_u32 s7, s71, 0
	s_nop 0
	global_load_dword v30, v4, s[6:7]
.Lp5_is_e3:
	s_add_i32 s10, s10, s9
	s_cmp_ge_u32 s10, 0x4080
	s_cbranch_scc1 .Lp5_iss_done
	s_mul_i32 s2, s10, 0x1a00
	s_add_u32 s2, s62, s2
	s_addc_u32 s3, s63, 0
	s_and_b32 s6, s10, 0x7ff
	global_load_ushort v20, v3, s[2:3]
	s_cmp_lt_u32 s10, 0x4000
	s_cbranch_scc0 .Lp5_is_s4
	s_cmp_eq_u32 s6, 0
	s_cbranch_scc1 .Lp5_is_e4
.Lp5_is_p4:
	s_sub_u32 s2, s2, 0x1a00
	s_subb_u32 s3, s3, 0
	s_nop 0
	global_load_ushort v31, v3, s[2:3]
	s_branch .Lp5_is_e4
.Lp5_is_s4:
	s_and_b32 s6, s10, 3
	s_cmp_lg_u32 s6, 0
	s_cbranch_scc1 .Lp5_is_p4
	s_sub_u32 s6, s10, 0x4000
	s_lshr_b32 s6, s6, 2
	s_mul_i32 s6, s6, 0x3400
	s_add_u32 s6, s70, s6
	s_addc_u32 s7, s71, 0
	s_nop 0
	global_load_dword v31, v4, s[6:7]
.Lp5_is_e4:
	s_add_i32 s10, s10, s9
	s_cmp_ge_u32 s10, 0x4080
	s_cbranch_scc1 .Lp5_iss_done
	s_mul_i32 s2, s10, 0x1a00
	s_add_u32 s2, s62, s2
	s_addc_u32 s3, s63, 0
	s_and_b32 s6, s10, 0x7ff
	global_load_ushort v21, v3, s[2:3]
	s_cmp_lt_u32 s10, 0x4000
	s_cbranch_scc0 .Lp5_is_s5
	s_cmp_eq_u32 s6, 0
	s_cbranch_scc1 .Lp5_is_e5
; __device__ __forceinline__ float bf2f(bf16 v) { return __uint_as_float((unsigned)v << 16); }
; __device__ __forceinline__ float prw_prev(const P& p, const bf16* PRW, int m, int col) {
;     if (m < MP) { return (m & (TP - 1)) == 0 ? 0.f : bf2f(PRW[(size_t)(m - 1) * RWP + col]); }
;     const int x = m - MP; return (x & 3) == 0 ? p.in[I_SSH][(size_t)(x >> 2) * RWP + col] : bf2f(PRW[(size_t)(m - 1) * RWP + col]);
; }
; __device__ __forceinline__ void lora_prep(const P& p, Frame& F) {
;     const bf16* PRW = (const bf16*)(p.ws + WS_PRW); bf16* AL = (bf16*)(p.ws + WS_ALORA); const float* mu = p.in[I_MU];
;     const int gt = F.bid * NTHR + F.tid, NGT = F.G * NTHR;
;     for (int i = gt; i < MPAD * 256; i += NGT) { const int m = i >> 8, k = i & 255; float v = 0.f;
;         if (m < MT) { const int col = 3072 + k; const float pc = bf2f(PRW[(size_t)m * RWP + col]), pp = prw_prev(p, PRW, m, col); const float xs = pc + (pp - pc) * mu[col];
.Lp5_is_p5:
	s_sub_u32 s2, s2, 0x1a00
	s_subb_u32 s3, s3, 0
	s_nop 0
	global_load_ushort v32, v3, s[2:3]
	s_branch .Lp5_is_e5
.Lp5_is_s5:
	s_and_b32 s6, s10, 3
	s_cmp_lg_u32 s6, 0
	s_cbranch_scc1 .Lp5_is_p5
	s_sub_u32 s6, s10, 0x4000
	s_lshr_b32 s6, s6, 2
	s_mul_i32 s6, s6, 0x3400
	s_add_u32 s6, s70, s6
	s_addc_u32 s7, s71, 0
	s_nop 0
	global_load_dword v32, v4, s[6:7]
.Lp5_is_e5:
	s_add_i32 s10, s10, s9
	s_cmp_ge_u32 s10, 0x4080
	s_cbranch_scc1 .Lp5_iss_done
	s_mul_i32 s2, s10, 0x1a00
	s_add_u32 s2, s62, s2
	s_addc_u32 s3, s63, 0
	s_and_b32 s6, s10, 0x7ff
	global_load_ushort v22, v3, s[2:3]
	s_cmp_lt_u32 s10, 0x4000
	s_cbranch_scc0 .Lp5_is_s6
	s_cmp_eq_u32 s6, 0
	s_cbranch_scc1 .Lp5_is_e6
.Lp5_is_p6:
	s_sub_u32 s2, s2, 0x1a00
	s_subb_u32 s3, s3, 0
	s_nop 0
	global_load_ushort v33, v3, s[2:3]
	s_branch .Lp5_is_e6
.Lp5_is_s6:
	s_and_b32 s6, s10, 3
	s_cmp_lg_u32 s6, 0
	s_cbranch_scc1 .Lp5_is_p6
	s_sub_u32 s6, s10, 0x4000
	s_lshr_b32 s6, s6, 2
	s_mul_i32 s6, s6, 0x3400
	s_add_u32 s6, s70, s6
	s_addc_u32 s7, s71, 0
	s_nop 0
	global_load_dword v33, v4, s[6:7]
.Lp5_is_e6:
	s_add_i32 s10, s10, s9
	s_cmp_ge_u32 s10, 0x4080
	s_cbranch_scc1 .Lp5_iss_done
	s_mul_i32 s2, s10, 0x1a00
	s_add_u32 s2, s62, s2
	s_addc_u32 s3, s63, 0
	s_and_b32 s6, s10, 0x7ff
	global_load_ushort v23, v3, s[2:3]
	s_cmp_lt_u32 s10, 0x4000
	s_cbranch_scc0 .Lp5_is_s7
	s_cmp_eq_u32 s6, 0
	s_cbranch_scc1 .Lp5_is_e7
.Lp5_is_p7:
	s_sub_u32 s2, s2, 0x1a00
	s_subb_u32 s3, s3, 0
	s_nop 0
	global_load_ushort v34, v3, s[2:3]
	s_branch .Lp5_is_e7
.Lp5_is_s7:
	s_and_b32 s6, s10, 3
	s_cmp_lg_u32 s6, 0
	s_cbranch_scc1 .Lp5_is_p7
	s_sub_u32 s6, s10, 0x4000
	s_lshr_b32 s6, s6, 2
	s_mul_i32 s6, s6, 0x3400
	s_add_u32 s6, s70, s6
	s_addc_u32 s7, s71, 0
	s_nop 0
	global_load_dword v34, v4, s[6:7]
.Lp5_is_e7:
	s_add_i32 s10, s10, s9
	s_cmp_ge_u32 s10, 0x4080
	s_cbranch_scc1 .Lp5_iss_done
	s_mul_i32 s2, s10, 0x1a00
	s_add_u32 s2, s62, s2
	s_addc_u32 s3, s63, 0
	s_and_b32 s6, s10, 0x7ff
	global_load_ushort v24, v3, s[2:3]
	s_cmp_lt_u32 s10, 0x4000
	s_cbranch_scc0 .Lp5_is_s8
	s_cmp_eq_u32 s6, 0
	s_cbranch_scc1 .Lp5_is_e8
.Lp5_is_p8:
	s_sub_u32 s2, s2, 0x1a00
	s_subb_u32 s3, s3, 0
	s_nop 0
	global_load_ushort v35, v3, s[2:3]
	s_branch .Lp5_is_e8
.Lp5_is_s8:
	s_and_b32 s6, s10, 3
	s_cmp_lg_u32 s6, 0
	s_cbranch_scc1 .Lp5_is_p8
	s_sub_u32 s6, s10, 0x4000
	s_lshr_b32 s6, s6, 2
	s_mul_i32 s6, s6, 0x3400
	s_add_u32 s6, s70, s6
	s_addc_u32 s7, s71, 0
	s_nop 0
	global_load_dword v35, v4, s[6:7]
.Lp5_is_e8:
	s_add_i32 s10, s10, s9
	s_cmp_ge_u32 s10, 0x4080
	s_cbranch_scc1 .Lp5_iss_done
	s_mul_i32 s2, s10, 0x1a00
	s_add_u32 s2, s62, s2
	s_addc_u32 s3, s63, 0
	s_and_b32 s6, s10, 0x7ff
	global_load_ushort v25, v3, s[2:3]
	s_cmp_lt_u32 s10, 0x4000
	s_cbranch_scc0 .Lp5_is_s9
	s_cmp_eq_u32 s6, 0
	s_cbranch_scc1 .Lp5_is_e9
.Lp5_is_p9:
	s_sub_u32 s2, s2, 0x1a00
	s_subb_u32 s3, s3, 0
	s_nop 0
	global_load_ushort v36, v3, s[2:3]
	s_branch .Lp5_is_e9
.Lp5_is_s9:
	s_and_b32 s6, s10, 3
	s_cmp_lg_u32 s6, 0
	s_cbranch_scc1 .Lp5_is_p9
	s_sub_u32 s6, s10, 0x4000
	s_lshr_b32 s6, s6, 2
	s_mul_i32 s6, s6, 0x3400
	s_add_u32 s6, s70, s6
	s_addc_u32 s7, s71, 0
	s_nop 0
	global_load_dword v36, v4, s[6:7]
.Lp5_is_e9:
	s_add_i32 s10, s10, s9
	s_cmp_ge_u32 s10, 0x4080
	s_cbranch_scc1 .Lp5_iss_done
	s_mul_i32 s2, s10, 0x1a00
	s_add_u32 s2, s62, s2
	s_addc_u32 s3, s63, 0
	s_and_b32 s6, s10, 0x7ff
	global_load_ushort v26, v3, s[2:3]
	s_cmp_lt_u32 s10, 0x4000
	s_cbranch_scc0 .Lp5_is_s10
	s_cmp_eq_u32 s6, 0
	s_cbranch_scc1 .Lp5_is_e10
.Lp5_is_p10:
	s_sub_u32 s2, s2, 0x1a00
	s_subb_u32 s3, s3, 0
	s_nop 0
	global_load_ushort v37, v3, s[2:3]
	s_branch .Lp5_is_e10
.Lp5_is_s10:
	s_and_b32 s6, s10, 3
	s_cmp_lg_u32 s6, 0
	s_cbranch_scc1 .Lp5_is_p10
	s_sub_u32 s6, s10, 0x4000
	s_lshr_b32 s6, s6, 2
	s_mul_i32 s6, s6, 0x3400
	s_add_u32 s6, s70, s6
	s_addc_u32 s7, s71, 0
	s_nop 0
	global_load_dword v37, v4, s[6:7]
.Lp5_is_e10:
	s_add_i32 s10, s10, s9
.Lp5_iss_done:
	s_waitcnt vmcnt(0)
	s_mov_b32 s10, s8
	s_cmp_ge_u32 s10, 0x4080
	s_cbranch_scc1 .Lp5_xs_done
	v_lshlrev_b32_e32 v16, 16, v16
	s_and_b32 s6, s10, 0x7ff
	s_cmp_lt_u32 s10, 0x4000
	s_cbranch_scc0 .Lp5_xs_s0
	s_cmp_eq_u32 s6, 0
	s_cbranch_scc0 .Lp5_xs_p0
	v_mov_b32_e32 v27, 0
	s_branch .Lp5_xs_e0
.Lp5_xs_s0:
	s_and_b32 s6, s10, 3
	s_cmp_lg_u32 s6, 0
	s_cbranch_scc0 .Lp5_xs_e0
.Lp5_xs_p0:
	v_lshlrev_b32_e32 v27, 16, v27
.Lp5_xs_e0:
	v_sub_f32_e32 v27, v27, v16
	v_fmac_f32_e32 v16, v27, v5
	s_add_i32 s10, s10, s9
	s_cmp_ge_u32 s10, 0x4080
	s_cbranch_scc1 .Lp5_xs_done
	v_lshlrev_b32_e32 v17, 16, v17
	s_and_b32 s6, s10, 0x7ff
	s_cmp_lt_u32 s10, 0x4000
	s_cbranch_scc0 .Lp5_xs_s1
	s_cmp_eq_u32 s6, 0
	s_cbranch_scc0 .Lp5_xs_p1
	v_mov_b32_e32 v28, 0
	s_branch .Lp5_xs_e1

; __device__ __forceinline__ float bf2f(bf16 v) { return __uint_as_float((unsigned)v << 16); }
; __device__ __forceinline__ float prw_prev(const P& p, const bf16* PRW, int m, int col) {
;     if (m < MP) { return (m & (TP - 1)) == 0 ? 0.f : bf2f(PRW[(size_t)(m - 1) * RWP + col]); }
;     const int x = m - MP; return (x & 3) == 0 ? p.in[I_SSH][(size_t)(x >> 2) * RWP + col] : bf2f(PRW[(size_t)(m - 1) * RWP + col]);
; }
; __device__ __forceinline__ void lora_prep(const P& p, Frame& F) {
;     const bf16* PRW = (const bf16*)(p.ws + WS_PRW); bf16* AL = (bf16*)(p.ws + WS_ALORA); const float* mu = p.in[I_MU];
;     const int gt = F.bid * NTHR + F.tid, NGT = F.G * NTHR;
;     for (int i = gt; i < MPAD * 256; i += NGT) { const int m = i >> 8, k = i & 255; float v = 0.f;
;         if (m < MT) { const int col = 3072 + k; const float pc = bf2f(PRW[(size_t)m * RWP + col]), pp = prw_prev(p, PRW, m, col); const float xs = pc + (pp - pc) * mu[col];
.Lp5_xs_p1:
	v_lshlrev_b32_e32 v28, 16, v28
.Lp5_xs_e1:
	v_sub_f32_e32 v28, v28, v17
	v_fmac_f32_e32 v17, v28, v5
	s_add_i32 s10, s10, s9
	s_cmp_ge_u32 s10, 0x4080
	s_cbranch_scc1 .Lp5_xs_done
	v_lshlrev_b32_e32 v18, 16, v18
	s_and_b32 s6, s10, 0x7ff
	s_cmp_lt_u32 s10, 0x4000
	s_cbranch_scc0 .Lp5_xs_s2
	s_cmp_eq_u32 s6, 0
	s_cbranch_scc0 .Lp5_xs_p2
	v_mov_b32_e32 v29, 0
	s_branch .Lp5_xs_e2

; __device__ __forceinline__ float bf2f(bf16 v) { return __uint_as_float((unsigned)v << 16); }
; __device__ __forceinline__ float prw_prev(const P& p, const bf16* PRW, int m, int col) {
;     if (m < MP) { return (m & (TP - 1)) == 0 ? 0.f : bf2f(PRW[(size_t)(m - 1) * RWP + col]); }
;     const int x = m - MP; return (x & 3) == 0 ? p.in[I_SSH][(size_t)(x >> 2) * RWP + col] : bf2f(PRW[(size_t)(m - 1) * RWP + col]);
; }
; __device__ __forceinline__ void lora_prep(const P& p, Frame& F) {
;     const bf16* PRW = (const bf16*)(p.ws + WS_PRW); bf16* AL = (bf16*)(p.ws + WS_ALORA); const float* mu = p.in[I_MU];
;     const int gt = F.bid * NTHR + F.tid, NGT = F.G * NTHR;
;     for (int i = gt; i < MPAD * 256; i += NGT) { const int m = i >> 8, k = i & 255; float v = 0.f;
;         if (m < MT) { const int col = 3072 + k; const float pc = bf2f(PRW[(size_t)m * RWP + col]), pp = prw_prev(p, PRW, m, col); const float xs = pc + (pp - pc) * mu[col];
.Lp5_xs_p2:
	v_lshlrev_b32_e32 v29, 16, v29
.Lp5_xs_e2:
	v_sub_f32_e32 v29, v29, v18
	v_fmac_f32_e32 v18, v29, v5
	s_add_i32 s10, s10, s9
	s_cmp_ge_u32 s10, 0x4080
	s_cbranch_scc1 .Lp5_xs_done
	v_lshlrev_b32_e32 v19, 16, v19
	s_and_b32 s6, s10, 0x7ff
	s_cmp_lt_u32 s10, 0x4000
	s_cbranch_scc0 .Lp5_xs_s3
	s_cmp_eq_u32 s6, 0
	s_cbranch_scc0 .Lp5_xs_p3
	v_mov_b32_e32 v30, 0
	s_branch .Lp5_xs_e3

; __device__ __forceinline__ float bf2f(bf16 v) { return __uint_as_float((unsigned)v << 16); }
; __device__ __forceinline__ float prw_prev(const P& p, const bf16* PRW, int m, int col) {
;     if (m < MP) { return (m & (TP - 1)) == 0 ? 0.f : bf2f(PRW[(size_t)(m - 1) * RWP + col]); }
;     const int x = m - MP; return (x & 3) == 0 ? p.in[I_SSH][(size_t)(x >> 2) * RWP + col] : bf2f(PRW[(size_t)(m - 1) * RWP + col]);
; }
; __device__ __forceinline__ void lora_prep(const P& p, Frame& F) {
;     const bf16* PRW = (const bf16*)(p.ws + WS_PRW); bf16* AL = (bf16*)(p.ws + WS_ALORA); const float* mu = p.in[I_MU];
;     const int gt = F.bid * NTHR + F.tid, NGT = F.G * NTHR;
;     for (int i = gt; i < MPAD * 256; i += NGT) { const int m = i >> 8, k = i & 255; float v = 0.f;
;         if (m < MT) { const int col = 3072 + k; const float pc = bf2f(PRW[(size_t)m * RWP + col]), pp = prw_prev(p, PRW, m, col); const float xs = pc + (pp - pc) * mu[col];
.Lp5_xs_p3:
	v_lshlrev_b32_e32 v30, 16, v30
.Lp5_xs_e3:
	v_sub_f32_e32 v30, v30, v19
	v_fmac_f32_e32 v19, v30, v5
	s_add_i32 s10, s10, s9
	s_cmp_ge_u32 s10, 0x4080
	s_cbranch_scc1 .Lp5_xs_done
	v_lshlrev_b32_e32 v20, 16, v20
	s_and_b32 s6, s10, 0x7ff
	s_cmp_lt_u32 s10, 0x4000
	s_cbranch_scc0 .Lp5_xs_s4
	s_cmp_eq_u32 s6, 0
	s_cbranch_scc0 .Lp5_xs_p4
	v_mov_b32_e32 v31, 0
	s_branch .Lp5_xs_e4

; __device__ __forceinline__ float bf2f(bf16 v) { return __uint_as_float((unsigned)v << 16); }
; __device__ __forceinline__ float prw_prev(const P& p, const bf16* PRW, int m, int col) {
;     if (m < MP) { return (m & (TP - 1)) == 0 ? 0.f : bf2f(PRW[(size_t)(m - 1) * RWP + col]); }
;     const int x = m - MP; return (x & 3) == 0 ? p.in[I_SSH][(size_t)(x >> 2) * RWP + col] : bf2f(PRW[(size_t)(m - 1) * RWP + col]);
; }
; __device__ __forceinline__ void lora_prep(const P& p, Frame& F) {
;     const bf16* PRW = (const bf16*)(p.ws + WS_PRW); bf16* AL = (bf16*)(p.ws + WS_ALORA); const float* mu = p.in[I_MU];
;     const int gt = F.bid * NTHR + F.tid, NGT = F.G * NTHR;
;     for (int i = gt; i < MPAD * 256; i += NGT) { const int m = i >> 8, k = i & 255; float v = 0.f;
;         if (m < MT) { const int col = 3072 + k; const float pc = bf2f(PRW[(size_t)m * RWP + col]), pp = prw_prev(p, PRW, m, col); const float xs = pc + (pp - pc) * mu[col];
.Lp5_xs_p4:
	v_lshlrev_b32_e32 v31, 16, v31
.Lp5_xs_e4:
	v_sub_f32_e32 v31, v31, v20
	v_fmac_f32_e32 v20, v31, v5
	s_add_i32 s10, s10, s9
	s_cmp_ge_u32 s10, 0x4080
	s_cbranch_scc1 .Lp5_xs_done
	v_lshlrev_b32_e32 v21, 16, v21
	s_and_b32 s6, s10, 0x7ff
	s_cmp_lt_u32 s10, 0x4000
	s_cbranch_scc0 .Lp5_xs_s5
	s_cmp_eq_u32 s6, 0
	s_cbranch_scc0 .Lp5_xs_p5
	v_mov_b32_e32 v32, 0
	s_branch .Lp5_xs_e5

; __device__ __forceinline__ float bf2f(bf16 v) { return __uint_as_float((unsigned)v << 16); }
; __device__ __forceinline__ float prw_prev(const P& p, const bf16* PRW, int m, int col) {
;     if (m < MP) { return (m & (TP - 1)) == 0 ? 0.f : bf2f(PRW[(size_t)(m - 1) * RWP + col]); }
;     const int x = m - MP; return (x & 3) == 0 ? p.in[I_SSH][(size_t)(x >> 2) * RWP + col] : bf2f(PRW[(size_t)(m - 1) * RWP + col]);
; }
; __device__ __forceinline__ void lora_prep(const P& p, Frame& F) {
;     const bf16* PRW = (const bf16*)(p.ws + WS_PRW); bf16* AL = (bf16*)(p.ws + WS_ALORA); const float* mu = p.in[I_MU];
;     const int gt = F.bid * NTHR + F.tid, NGT = F.G * NTHR;
;     for (int i = gt; i < MPAD * 256; i += NGT) { const int m = i >> 8, k = i & 255; float v = 0.f;
;         if (m < MT) { const int col = 3072 + k; const float pc = bf2f(PRW[(size_t)m * RWP + col]), pp = prw_prev(p, PRW, m, col); const float xs = pc + (pp - pc) * mu[col];
.Lp5_xs_p5:
	v_lshlrev_b32_e32 v32, 16, v32
.Lp5_xs_e5:
	v_sub_f32_e32 v32, v32, v21
	v_fmac_f32_e32 v21, v32, v5
	s_add_i32 s10, s10, s9
	s_cmp_ge_u32 s10, 0x4080
	s_cbranch_scc1 .Lp5_xs_done
	v_lshlrev_b32_e32 v22, 16, v22
	s_and_b32 s6, s10, 0x7ff
	s_cmp_lt_u32 s10, 0x4000
	s_cbranch_scc0 .Lp5_xs_s6
	s_cmp_eq_u32 s6, 0
	s_cbranch_scc0 .Lp5_xs_p6
	v_mov_b32_e32 v33, 0
	s_branch .Lp5_xs_e6

; __device__ __forceinline__ float bf2f(bf16 v) { return __uint_as_float((unsigned)v << 16); }
; __device__ __forceinline__ float prw_prev(const P& p, const bf16* PRW, int m, int col) {
;     if (m < MP) { return (m & (TP - 1)) == 0 ? 0.f : bf2f(PRW[(size_t)(m - 1) * RWP + col]); }
;     const int x = m - MP; return (x & 3) == 0 ? p.in[I_SSH][(size_t)(x >> 2) * RWP + col] : bf2f(PRW[(size_t)(m - 1) * RWP + col]);
; }
; __device__ __forceinline__ void lora_prep(const P& p, Frame& F) {
;     const bf16* PRW = (const bf16*)(p.ws + WS_PRW); bf16* AL = (bf16*)(p.ws + WS_ALORA); const float* mu = p.in[I_MU];
;     const int gt = F.bid * NTHR + F.tid, NGT = F.G * NTHR;
;     for (int i = gt; i < MPAD * 256; i += NGT) { const int m = i >> 8, k = i & 255; float v = 0.f;
;         if (m < MT) { const int col = 3072 + k; const float pc = bf2f(PRW[(size_t)m * RWP + col]), pp = prw_prev(p, PRW, m, col); const float xs = pc + (pp - pc) * mu[col];
.Lp5_xs_p6:
	v_lshlrev_b32_e32 v33, 16, v33
.Lp5_xs_e6:
	v_sub_f32_e32 v33, v33, v22
	v_fmac_f32_e32 v22, v33, v5
	s_add_i32 s10, s10, s9
	s_cmp_ge_u32 s10, 0x4080
	s_cbranch_scc1 .Lp5_xs_done
	v_lshlrev_b32_e32 v23, 16, v23
	s_and_b32 s6, s10, 0x7ff
	s_cmp_lt_u32 s10, 0x4000
	s_cbranch_scc0 .Lp5_xs_s7
	s_cmp_eq_u32 s6, 0
	s_cbranch_scc0 .Lp5_xs_p7
	v_mov_b32_e32 v34, 0
	s_branch .Lp5_xs_e7

; __device__ __forceinline__ float bf2f(bf16 v) { return __uint_as_float((unsigned)v << 16); }
; __device__ __forceinline__ float prw_prev(const P& p, const bf16* PRW, int m, int col) {
;     if (m < MP) { return (m & (TP - 1)) == 0 ? 0.f : bf2f(PRW[(size_t)(m - 1) * RWP + col]); }
;     const int x = m - MP; return (x & 3) == 0 ? p.in[I_SSH][(size_t)(x >> 2) * RWP + col] : bf2f(PRW[(size_t)(m - 1) * RWP + col]);
; }
; __device__ __forceinline__ void lora_prep(const P& p, Frame& F) {
;     const bf16* PRW = (const bf16*)(p.ws + WS_PRW); bf16* AL = (bf16*)(p.ws + WS_ALORA); const float* mu = p.in[I_MU];
;     const int gt = F.bid * NTHR + F.tid, NGT = F.G * NTHR;
;     for (int i = gt; i < MPAD * 256; i += NGT) { const int m = i >> 8, k = i & 255; float v = 0.f;
;         if (m < MT) { const int col = 3072 + k; const float pc = bf2f(PRW[(size_t)m * RWP + col]), pp = prw_prev(p, PRW, m, col); const float xs = pc + (pp - pc) * mu[col];
.Lp5_xs_p7:
	v_lshlrev_b32_e32 v34, 16, v34
.Lp5_xs_e7:
	v_sub_f32_e32 v34, v34, v23
	v_fmac_f32_e32 v23, v34, v5
	s_add_i32 s10, s10, s9
	s_cmp_ge_u32 s10, 0x4080
	s_cbranch_scc1 .Lp5_xs_done
	v_lshlrev_b32_e32 v24, 16, v24
	s_and_b32 s6, s10, 0x7ff
	s_cmp_lt_u32 s10, 0x4000
	s_cbranch_scc0 .Lp5_xs_s8
	s_cmp_eq_u32 s6, 0
	s_cbranch_scc0 .Lp5_xs_p8
	v_mov_b32_e32 v35, 0
	s_branch .Lp5_xs_e8

; __device__ __forceinline__ float bf2f(bf16 v) { return __uint_as_float((unsigned)v << 16); }
; __device__ __forceinline__ float prw_prev(const P& p, const bf16* PRW, int m, int col) {
;     if (m < MP) { return (m & (TP - 1)) == 0 ? 0.f : bf2f(PRW[(size_t)(m - 1) * RWP + col]); }
;     const int x = m - MP; return (x & 3) == 0 ? p.in[I_SSH][(size_t)(x >> 2) * RWP + col] : bf2f(PRW[(size_t)(m - 1) * RWP + col]);
; }
; __device__ __forceinline__ void lora_prep(const P& p, Frame& F) {
;     const bf16* PRW = (const bf16*)(p.ws + WS_PRW); bf16* AL = (bf16*)(p.ws + WS_ALORA); const float* mu = p.in[I_MU];
;     const int gt = F.bid * NTHR + F.tid, NGT = F.G * NTHR;
;     for (int i = gt; i < MPAD * 256; i += NGT) { const int m = i >> 8, k = i & 255; float v = 0.f;
;         if (m < MT) { const int col = 3072 + k; const float pc = bf2f(PRW[(size_t)m * RWP + col]), pp = prw_prev(p, PRW, m, col); const float xs = pc + (pp - pc) * mu[col];
.Lp5_xs_p8:
	v_lshlrev_b32_e32 v35, 16, v35
.Lp5_xs_e8:
	v_sub_f32_e32 v35, v35, v24
	v_fmac_f32_e32 v24, v35, v5
	s_add_i32 s10, s10, s9
	s_cmp_ge_u32 s10, 0x4080
	s_cbranch_scc1 .Lp5_xs_done
	v_lshlrev_b32_e32 v25, 16, v25
	s_and_b32 s6, s10, 0x7ff
	s_cmp_lt_u32 s10, 0x4000
	s_cbranch_scc0 .Lp5_xs_s9
	s_cmp_eq_u32 s6, 0
	s_cbranch_scc0 .Lp5_xs_p9
	v_mov_b32_e32 v36, 0
	s_branch .Lp5_xs_e9

; __device__ __forceinline__ float bf2f(bf16 v) { return __uint_as_float((unsigned)v << 16); }
; __device__ __forceinline__ float prw_prev(const P& p, const bf16* PRW, int m, int col) {
;     if (m < MP) { return (m & (TP - 1)) == 0 ? 0.f : bf2f(PRW[(size_t)(m - 1) * RWP + col]); }
;     const int x = m - MP; return (x & 3) == 0 ? p.in[I_SSH][(size_t)(x >> 2) * RWP + col] : bf2f(PRW[(size_t)(m - 1) * RWP + col]);
; }
; __device__ __forceinline__ void lora_prep(const P& p, Frame& F) {
;     const bf16* PRW = (const bf16*)(p.ws + WS_PRW); bf16* AL = (bf16*)(p.ws + WS_ALORA); const float* mu = p.in[I_MU];
;     const int gt = F.bid * NTHR + F.tid, NGT = F.G * NTHR;
;     for (int i = gt; i < MPAD * 256; i += NGT) { const int m = i >> 8, k = i & 255; float v = 0.f;
;         if (m < MT) { const int col = 3072 + k; const float pc = bf2f(PRW[(size_t)m * RWP + col]), pp = prw_prev(p, PRW, m, col); const float xs = pc + (pp - pc) * mu[col];
.Lp5_xs_p9:
	v_lshlrev_b32_e32 v36, 16, v36
.Lp5_xs_e9:
	v_sub_f32_e32 v36, v36, v25
	v_fmac_f32_e32 v25, v36, v5
	s_add_i32 s10, s10, s9
	s_cmp_ge_u32 s10, 0x4080
	s_cbranch_scc1 .Lp5_xs_done
	v_lshlrev_b32_e32 v26, 16, v26
	s_and_b32 s6, s10, 0x7ff
	s_cmp_lt_u32 s10, 0x4000
	s_cbranch_scc0 .Lp5_xs_s10
	s_cmp_eq_u32 s6, 0
	s_cbranch_scc0 .Lp5_xs_p10
	v_mov_b32_e32 v37, 0
	s_branch .Lp5_xs_e10

; __device__ __forceinline__ float bf2f(bf16 v) { return __uint_as_float((unsigned)v << 16); }
; __device__ __forceinline__ float sigmoidf_(float x) { return __builtin_amdgcn_rcpf(1.0f + __builtin_amdgcn_exp2f(-1.4426950408889634f * x)); }
; __device__ __forceinline__ void lora_prep(const P& p, Frame& F) {
;     ...
;         if (m < MT) { const int col = 3072 + k; const float pc = bf2f(PRW[(size_t)m * RWP + col]), pp = prw_prev(p, PRW, m, col); const float xs = pc + (pp - pc) * mu[col];
;             v = k < 64 ? 1.0f - 2.0f / (1.0f + __expf(2.0f * xs)) : (k < 128 ? xs : sigmoidf_(xs)); }
.Lp5_xs_p10:
	v_lshlrev_b32_e32 v37, 16, v37
.Lp5_xs_e10:
	v_sub_f32_e32 v37, v37, v26
	v_fmac_f32_e32 v26, v37, v5
	s_add_i32 s10, s10, s9
.Lp5_xs_done:
	s_cmp_eq_u32 s11, 1
	s_cbranch_scc1 .Lp5_act_done
	s_cmp_eq_u32 s11, 0
	s_cbranch_scc1 .Lp5_tanh
	v_mul_f32_e32 v16, 0xbfb8aa3b, v16
	v_exp_f32_e32 v16, v16
	s_nop 0
	v_add_f32_e32 v16, 1.0, v16
	v_rcp_f32_e32 v16, v16
	s_nop 0
	v_mul_f32_e32 v17, 0xbfb8aa3b, v17
	v_exp_f32_e32 v17, v17
	s_nop 0
	v_add_f32_e32 v17, 1.0, v17
	v_rcp_f32_e32 v17, v17
	s_nop 0
	v_mul_f32_e32 v18, 0xbfb8aa3b, v18
	v_exp_f32_e32 v18, v18
	s_nop 0
	v_add_f32_e32 v18, 1.0, v18
	v_rcp_f32_e32 v18, v18
	s_nop 0
	v_mul_f32_e32 v19, 0xbfb8aa3b, v19
	v_exp_f32_e32 v19, v19
	s_nop 0
	v_add_f32_e32 v19, 1.0, v19
	v_rcp_f32_e32 v19, v19
	s_nop 0
	v_mul_f32_e32 v20, 0xbfb8aa3b, v20
	v_exp_f32_e32 v20, v20
	s_nop 0
	v_add_f32_e32 v20, 1.0, v20
	v_rcp_f32_e32 v20, v20
	s_nop 0
	v_mul_f32_e32 v21, 0xbfb8aa3b, v21
	v_exp_f32_e32 v21, v21
	s_nop 0
	v_add_f32_e32 v21, 1.0, v21
	v_rcp_f32_e32 v21, v21
	s_nop 0
	v_mul_f32_e32 v22, 0xbfb8aa3b, v22
	v_exp_f32_e32 v22, v22
	s_nop 0
	v_add_f32_e32 v22, 1.0, v22
	v_rcp_f32_e32 v22, v22
	s_nop 0
	v_mul_f32_e32 v23, 0xbfb8aa3b, v23
	v_exp_f32_e32 v23, v23
	s_nop 0
	v_add_f32_e32 v23, 1.0, v23
	v_rcp_f32_e32 v23, v23
	s_nop 0
	v_mul_f32_e32 v24, 0xbfb8aa3b, v24
	v_exp_f32_e32 v24, v24
	s_nop 0
	v_add_f32_e32 v24, 1.0, v24
	v_rcp_f32_e32 v24, v24
	s_nop 0
	v_mul_f32_e32 v25, 0xbfb8aa3b, v25
	v_exp_f32_e32 v25, v25
	s_nop 0
	v_add_f32_e32 v25, 1.0, v25
	v_rcp_f32_e32 v25, v25
	s_nop 0
	v_mul_f32_e32 v26, 0xbfb8aa3b, v26
	v_exp_f32_e32 v26, v26
	s_nop 0
	v_add_f32_e32 v26, 1.0, v26
	v_rcp_f32_e32 v26, v26
	s_nop 0
	s_branch .Lp5_act_done
.Lp5_tanh:
	v_add_f32_e32 v16, v16, v16
	v_mul_f32_e32 v16, 0x3fb8aa3b, v16
	v_exp_f32_e32 v16, v16
	s_nop 0
	v_add_f32_e32 v16, 1.0, v16
	v_div_scale_f32 v7, s[18:19], v16, v16, 2.0
	v_rcp_f32_e32 v8, v7
	v_div_scale_f32 v9, vcc, 2.0, v16, 2.0
	v_fma_f32 v10, -v7, v8, 1.0
	v_fmac_f32_e32 v8, v10, v8
	v_mul_f32_e32 v10, v9, v8
	v_fma_f32 v11, -v7, v10, v9
	v_fmac_f32_e32 v10, v11, v8
	v_fma_f32 v7, -v7, v10, v9
	v_div_fmas_f32 v7, v7, v8, v10
	v_div_fixup_f32 v16, v7, v16, 2.0
	v_sub_f32_e32 v16, 1.0, v16
	v_add_f32_e32 v17, v17, v17
	v_mul_f32_e32 v17, 0x3fb8aa3b, v17
	v_exp_f32_e32 v17, v17
	s_nop 0
	v_add_f32_e32 v17, 1.0, v17
	v_div_scale_f32 v7, s[18:19], v17, v17, 2.0
	v_rcp_f32_e32 v8, v7
	v_div_scale_f32 v9, vcc, 2.0, v17, 2.0
	v_fma_f32 v10, -v7, v8, 1.0
	v_fmac_f32_e32 v8, v10, v8
	v_mul_f32_e32 v10, v9, v8
	v_fma_f32 v11, -v7, v10, v9
	v_fmac_f32_e32 v10, v11, v8
	v_fma_f32 v7, -v7, v10, v9
	v_div_fmas_f32 v7, v7, v8, v10
	v_div_fixup_f32 v17, v7, v17, 2.0
	v_sub_f32_e32 v17, 1.0, v17
	v_add_f32_e32 v18, v18, v18
	v_mul_f32_e32 v18, 0x3fb8aa3b, v18
	v_exp_f32_e32 v18, v18
	s_nop 0
	v_add_f32_e32 v18, 1.0, v18
	v_div_scale_f32 v7, s[18:19], v18, v18, 2.0
	v_rcp_f32_e32 v8, v7
	v_div_scale_f32 v9, vcc, 2.0, v18, 2.0
	v_fma_f32 v10, -v7, v8, 1.0
	v_fmac_f32_e32 v8, v10, v8
	v_mul_f32_e32 v10, v9, v8
	v_fma_f32 v11, -v7, v10, v9
	v_fmac_f32_e32 v10, v11, v8
	v_fma_f32 v7, -v7, v10, v9
	v_div_fmas_f32 v7, v7, v8, v10
	v_div_fixup_f32 v18, v7, v18, 2.0
	v_sub_f32_e32 v18, 1.0, v18
	v_add_f32_e32 v19, v19, v19
	v_mul_f32_e32 v19, 0x3fb8aa3b, v19
	v_exp_f32_e32 v19, v19
	s_nop 0
	v_add_f32_e32 v19, 1.0, v19
	v_div_scale_f32 v7, s[18:19], v19, v19, 2.0
	v_rcp_f32_e32 v8, v7
	v_div_scale_f32 v9, vcc, 2.0, v19, 2.0
	v_fma_f32 v10, -v7, v8, 1.0
	v_fmac_f32_e32 v8, v10, v8
	v_mul_f32_e32 v10, v9, v8
	v_fma_f32 v11, -v7, v10, v9
	v_fmac_f32_e32 v10, v11, v8
	v_fma_f32 v7, -v7, v10, v9
	v_div_fmas_f32 v7, v7, v8, v10
	v_div_fixup_f32 v19, v7, v19, 2.0
	v_sub_f32_e32 v19, 1.0, v19
	v_add_f32_e32 v20, v20, v20
	v_mul_f32_e32 v20, 0x3fb8aa3b, v20
	v_exp_f32_e32 v20, v20
	s_nop 0
	v_add_f32_e32 v20, 1.0, v20
	v_div_scale_f32 v7, s[18:19], v20, v20, 2.0
	v_rcp_f32_e32 v8, v7
	v_div_scale_f32 v9, vcc, 2.0, v20, 2.0
	v_fma_f32 v10, -v7, v8, 1.0
	v_fmac_f32_e32 v8, v10, v8
	v_mul_f32_e32 v10, v9, v8
	v_fma_f32 v11, -v7, v10, v9
	v_fmac_f32_e32 v10, v11, v8
	v_fma_f32 v7, -v7, v10, v9
	v_div_fmas_f32 v7, v7, v8, v10
	v_div_fixup_f32 v20, v7, v20, 2.0
	v_sub_f32_e32 v20, 1.0, v20
	v_add_f32_e32 v21, v21, v21
	v_mul_f32_e32 v21, 0x3fb8aa3b, v21
	v_exp_f32_e32 v21, v21
	s_nop 0
	v_add_f32_e32 v21, 1.0, v21
	v_div_scale_f32 v7, s[18:19], v21, v21, 2.0
	v_rcp_f32_e32 v8, v7
	v_div_scale_f32 v9, vcc, 2.0, v21, 2.0
	v_fma_f32 v10, -v7, v8, 1.0
	v_fmac_f32_e32 v8, v10, v8
	v_mul_f32_e32 v10, v9, v8
	v_fma_f32 v11, -v7, v10, v9
	v_fmac_f32_e32 v10, v11, v8
	v_fma_f32 v7, -v7, v10, v9
	v_div_fmas_f32 v7, v7, v8, v10
	v_div_fixup_f32 v21, v7, v21, 2.0
	v_sub_f32_e32 v21, 1.0, v21
	v_add_f32_e32 v22, v22, v22
	v_mul_f32_e32 v22, 0x3fb8aa3b, v22
	v_exp_f32_e32 v22, v22
	s_nop 0
	v_add_f32_e32 v22, 1.0, v22
	v_div_scale_f32 v7, s[18:19], v22, v22, 2.0
	v_rcp_f32_e32 v8, v7
	v_div_scale_f32 v9, vcc, 2.0, v22, 2.0
	v_fma_f32 v10, -v7, v8, 1.0
	v_fmac_f32_e32 v8, v10, v8
	v_mul_f32_e32 v10, v9, v8
	v_fma_f32 v11, -v7, v10, v9
	v_fmac_f32_e32 v10, v11, v8
	v_fma_f32 v7, -v7, v10, v9
	v_div_fmas_f32 v7, v7, v8, v10
	v_div_fixup_f32 v22, v7, v22, 2.0
	v_sub_f32_e32 v22, 1.0, v22
	v_add_f32_e32 v23, v23, v23
	v_mul_f32_e32 v23, 0x3fb8aa3b, v23
	v_exp_f32_e32 v23, v23
	s_nop 0
	v_add_f32_e32 v23, 1.0, v23
	v_div_scale_f32 v7, s[18:19], v23, v23, 2.0
	v_rcp_f32_e32 v8, v7
	v_div_scale_f32 v9, vcc, 2.0, v23, 2.0
	v_fma_f32 v10, -v7, v8, 1.0
	v_fmac_f32_e32 v8, v10, v8
	v_mul_f32_e32 v10, v9, v8
	v_fma_f32 v11, -v7, v10, v9
	v_fmac_f32_e32 v10, v11, v8
	v_fma_f32 v7, -v7, v10, v9
; __device__ __forceinline__ unsigned pk2(float lo, float hi) { const bfx2 b = __builtin_convertvector((f32x2){lo, hi}, bfx2); return __builtin_bit_cast(unsigned, b); }
; __device__ __forceinline__ float bf2f(bf16 v) { return __uint_as_float((unsigned)v << 16); }
; __device__ __forceinline__ float sigmoidf_(float x) { return __builtin_amdgcn_rcpf(1.0f + __builtin_amdgcn_exp2f(-1.4426950408889634f * x)); }
; __device__ __forceinline__ void lora_prep(const P& p, Frame& F) {
;     ...
;         if (m < MT) { const int col = 3072 + k; const float pc = bf2f(PRW[(size_t)m * RWP + col]), pp = prw_prev(p, PRW, m, col); const float xs = pc + (pp - pc) * mu[col];
;             v = k < 64 ? 1.0f - 2.0f / (1.0f + __expf(2.0f * xs)) : (k < 128 ? xs : sigmoidf_(xs)); }
;         AL[i] = (bf16)(pk2(v, 0.f) & 0xffffu); }
	v_div_fmas_f32 v7, v7, v8, v10
	v_div_fixup_f32 v23, v7, v23, 2.0
	v_sub_f32_e32 v23, 1.0, v23
	v_add_f32_e32 v24, v24, v24
	v_mul_f32_e32 v24, 0x3fb8aa3b, v24
	v_exp_f32_e32 v24, v24
	s_nop 0
	v_add_f32_e32 v24, 1.0, v24
	v_div_scale_f32 v7, s[18:19], v24, v24, 2.0
	v_rcp_f32_e32 v8, v7
	v_div_scale_f32 v9, vcc, 2.0, v24, 2.0
	v_fma_f32 v10, -v7, v8, 1.0
	v_fmac_f32_e32 v8, v10, v8
	v_mul_f32_e32 v10, v9, v8
	v_fma_f32 v11, -v7, v10, v9
	v_fmac_f32_e32 v10, v11, v8
	v_fma_f32 v7, -v7, v10, v9
	v_div_fmas_f32 v7, v7, v8, v10
	v_div_fixup_f32 v24, v7, v24, 2.0
	v_sub_f32_e32 v24, 1.0, v24
	v_add_f32_e32 v25, v25, v25
	v_mul_f32_e32 v25, 0x3fb8aa3b, v25
	v_exp_f32_e32 v25, v25
	s_nop 0
	v_add_f32_e32 v25, 1.0, v25
	v_div_scale_f32 v7, s[18:19], v25, v25, 2.0
	v_rcp_f32_e32 v8, v7
	v_div_scale_f32 v9, vcc, 2.0, v25, 2.0
	v_fma_f32 v10, -v7, v8, 1.0
	v_fmac_f32_e32 v8, v10, v8
	v_mul_f32_e32 v10, v9, v8
	v_fma_f32 v11, -v7, v10, v9
	v_fmac_f32_e32 v10, v11, v8
	v_fma_f32 v7, -v7, v10, v9
	v_div_fmas_f32 v7, v7, v8, v10
	v_div_fixup_f32 v25, v7, v25, 2.0
	v_sub_f32_e32 v25, 1.0, v25
	v_add_f32_e32 v26, v26, v26
	v_mul_f32_e32 v26, 0x3fb8aa3b, v26
	v_exp_f32_e32 v26, v26
	s_nop 0
	v_add_f32_e32 v26, 1.0, v26
	v_div_scale_f32 v7, s[18:19], v26, v26, 2.0
	v_rcp_f32_e32 v8, v7
	v_div_scale_f32 v9, vcc, 2.0, v26, 2.0
	v_fma_f32 v10, -v7, v8, 1.0
	v_fmac_f32_e32 v8, v10, v8
	v_mul_f32_e32 v10, v9, v8
	v_fma_f32 v11, -v7, v10, v9
	v_fmac_f32_e32 v10, v11, v8
	v_fma_f32 v7, -v7, v10, v9
	v_div_fmas_f32 v7, v7, v8, v10
	v_div_fixup_f32 v26, v7, v26, 2.0
	v_sub_f32_e32 v26, 1.0, v26
.Lp5_act_done:
	s_mov_b32 s10, s8
	s_cmp_ge_u32 s10, 0x4100
	s_cbranch_scc1 .Lp5_end
	s_lshl_b32 s2, s10, 9
	s_add_u32 s2, s14, s2
	s_addc_u32 s3, s15, 0
	s_cmp_ge_u32 s10, 0x4080
	s_cbranch_scc0 .Lp5_st_v0
	v_mov_b32_e32 v16, 0
.Lp5_st_v0:
	v_cvt_pk_bf16_f32 v6, v16, v16
	s_add_i32 s10, s10, s9
	global_store_short v2, v6, s[2:3]
	s_cmp_ge_u32 s10, 0x4100
	s_cbranch_scc1 .Lp5_end
	s_lshl_b32 s2, s10, 9
	s_add_u32 s2, s14, s2
	s_addc_u32 s3, s15, 0
	s_cmp_ge_u32 s10, 0x4080
	s_cbranch_scc0 .Lp5_st_v1
	v_mov_b32_e32 v17, 0
.Lp5_st_v1:
	v_cvt_pk_bf16_f32 v6, v17, v17
	s_add_i32 s10, s10, s9
	global_store_short v2, v6, s[2:3]
	s_cmp_ge_u32 s10, 0x4100
	s_cbranch_scc1 .Lp5_end
	s_lshl_b32 s2, s10, 9
	s_add_u32 s2, s14, s2
	s_addc_u32 s3, s15, 0
	s_cmp_ge_u32 s10, 0x4080
	s_cbranch_scc0 .Lp5_st_v2
	v_mov_b32_e32 v18, 0
.Lp5_st_v2:
	v_cvt_pk_bf16_f32 v6, v18, v18
	s_add_i32 s10, s10, s9
	global_store_short v2, v6, s[2:3]
	s_cmp_ge_u32 s10, 0x4100
	s_cbranch_scc1 .Lp5_end
	s_lshl_b32 s2, s10, 9
	s_add_u32 s2, s14, s2
	s_addc_u32 s3, s15, 0
	s_cmp_ge_u32 s10, 0x4080
	s_cbranch_scc0 .Lp5_st_v3
	v_mov_b32_e32 v19, 0
.Lp5_st_v3:
	v_cvt_pk_bf16_f32 v6, v19, v19
	s_add_i32 s10, s10, s9
	global_store_short v2, v6, s[2:3]
	s_cmp_ge_u32 s10, 0x4100
	s_cbranch_scc1 .Lp5_end
	s_lshl_b32 s2, s10, 9
	s_add_u32 s2, s14, s2
	s_addc_u32 s3, s15, 0
	s_cmp_ge_u32 s10, 0x4080
	s_cbranch_scc0 .Lp5_st_v4
	v_mov_b32_e32 v20, 0
.Lp5_st_v4:
	v_cvt_pk_bf16_f32 v6, v20, v20
	s_add_i32 s10, s10, s9
	global_store_short v2, v6, s[2:3]
	s_cmp_ge_u32 s10, 0x4100
	s_cbranch_scc1 .Lp5_end
	s_lshl_b32 s2, s10, 9
	s_add_u32 s2, s14, s2
	s_addc_u32 s3, s15, 0
	s_cmp_ge_u32 s10, 0x4080
	s_cbranch_scc0 .Lp5_st_v5
	v_mov_b32_e32 v21, 0
.Lp5_st_v5:
	v_cvt_pk_bf16_f32 v6, v21, v21
	s_add_i32 s10, s10, s9
	global_store_short v2, v6, s[2:3]
	s_cmp_ge_u32 s10, 0x4100
	s_cbranch_scc1 .Lp5_end
	s_lshl_b32 s2, s10, 9
	s_add_u32 s2, s14, s2
	s_addc_u32 s3, s15, 0
	s_cmp_ge_u32 s10, 0x4080
	s_cbranch_scc0 .Lp5_st_v6
	v_mov_b32_e32 v22, 0
; __device__ __forceinline__ unsigned pk2(float lo, float hi) { const bfx2 b = __builtin_convertvector((f32x2){lo, hi}, bfx2); return __builtin_bit_cast(unsigned, b); }
; __device__ __forceinline__ float bf2f(bf16 v) { return __uint_as_float((unsigned)v << 16); }
; __device__ __forceinline__ float sigmoidf_(float x) { return __builtin_amdgcn_rcpf(1.0f + __builtin_amdgcn_exp2f(-1.4426950408889634f * x)); }
; __device__ __forceinline__ void xcd_barrier(const XcdBarrier& b) {
;     asm volatile("s_waitcnt vmcnt(0)" ::: "memory");
;     __syncthreads();
;     if (threadIdx.x == 0) {
;         unsigned* bar = b.bar;
;         __builtin_amdgcn_s_waitcnt(0);
;         unsigned nloc = b.st[0], nx = b.st[1];
;         if (nloc == 0u) { xcd_barrier_complete(bar, b.x, nloc, nx); b.st[0] = nloc; b.st[1] = nx; }
; __device__ __forceinline__ void lora_prep(const P& p, Frame& F) {
;     ...
;     for (int i = gt; i < MPAD * 256; i += NGT) { const int m = i >> 8, k = i & 255; float v = 0.f;
;         if (m < MT) { const int col = 3072 + k; const float pc = bf2f(PRW[(size_t)m * RWP + col]), pp = prw_prev(p, PRW, m, col); const float xs = pc + (pp - pc) * mu[col];
;             v = k < 64 ? 1.0f - 2.0f / (1.0f + __expf(2.0f * xs)) : (k < 128 ? xs : sigmoidf_(xs)); }
;         AL[i] = (bf16)(pk2(v, 0.f) & 0xffffu); }
.Lp5_st_v6:
	v_cvt_pk_bf16_f32 v6, v22, v22
	s_add_i32 s10, s10, s9
	global_store_short v2, v6, s[2:3]
	s_cmp_ge_u32 s10, 0x4100
	s_cbranch_scc1 .Lp5_end
	s_lshl_b32 s2, s10, 9
	s_add_u32 s2, s14, s2
	s_addc_u32 s3, s15, 0
	s_cmp_ge_u32 s10, 0x4080
	s_cbranch_scc0 .Lp5_st_v7
	v_mov_b32_e32 v23, 0
.Lp5_st_v7:
	v_cvt_pk_bf16_f32 v6, v23, v23
	s_add_i32 s10, s10, s9
	global_store_short v2, v6, s[2:3]
	s_cmp_ge_u32 s10, 0x4100
	s_cbranch_scc1 .Lp5_end
	s_lshl_b32 s2, s10, 9
	s_add_u32 s2, s14, s2
	s_addc_u32 s3, s15, 0
	s_cmp_ge_u32 s10, 0x4080
	s_cbranch_scc0 .Lp5_st_v8
	v_mov_b32_e32 v24, 0
.Lp5_st_v8:
	v_cvt_pk_bf16_f32 v6, v24, v24
	s_add_i32 s10, s10, s9
	global_store_short v2, v6, s[2:3]
	s_cmp_ge_u32 s10, 0x4100
	s_cbranch_scc1 .Lp5_end
	s_lshl_b32 s2, s10, 9
	s_add_u32 s2, s14, s2
	s_addc_u32 s3, s15, 0
	s_cmp_ge_u32 s10, 0x4080
	s_cbranch_scc0 .Lp5_st_v9
	v_mov_b32_e32 v25, 0
.Lp5_st_v9:
	v_cvt_pk_bf16_f32 v6, v25, v25
	s_add_i32 s10, s10, s9
	global_store_short v2, v6, s[2:3]
	s_cmp_ge_u32 s10, 0x4100
	s_cbranch_scc1 .Lp5_end
	s_lshl_b32 s2, s10, 9
	s_add_u32 s2, s14, s2
	s_addc_u32 s3, s15, 0
	s_cmp_ge_u32 s10, 0x4080
	s_cbranch_scc0 .Lp5_st_v10
	v_mov_b32_e32 v26, 0
.Lp5_st_v10:
	v_cvt_pk_bf16_f32 v6, v26, v26
	s_add_i32 s10, s10, s9
	global_store_short v2, v6, s[2:3]
	s_mov_b32 s8, s10
	s_cmp_lt_u32 s8, 0x4100
	s_cbranch_scc1 .Lp5_trip
.Lp5_end:
.LBB0_1361:
	s_or_b64 exec, exec, s[4:5]
	s_waitcnt vmcnt(0)
	s_waitcnt vmcnt(63) expcnt(7) lgkmcnt(15)
	s_barrier
	s_mov_b64 s[0:1], exec
	v_readlane_b32 s2, v253, 25
	v_readlane_b32 s3, v253, 26
	s_and_b64 s[2:3], s[0:1], s[2:3]
	s_mov_b64 exec, s[2:3]
	s_cbranch_execz .LBB0_1413
	s_add_i32 s2, 0, 0x23f20
	v_mov_b32_e32 v2, s2
	s_waitcnt vmcnt(0) expcnt(0) lgkmcnt(0)
	ds_read_b32 v4, v2
	s_add_i32 s2, 0, 0x23f24
	v_mov_b32_e32 v2, s2
	ds_read_b32 v2, v2
	s_waitcnt lgkmcnt(1)
	v_cmp_ne_u32_e32 vcc, 0, v4
	s_cbranch_vccnz .LBB0_1377
	v_readlane_b32 s4, v253, 2
	v_readlane_b32 s5, v253, 3
	v_readlane_b32 s36, v253, 32
	s_load_dwordx2 s[2:3], s[4:5], 0x4
	v_readlane_b32 s50, v253, 46
	v_readlane_b32 s51, v253, 47
	s_add_u32 s4, s50, 0x4200
	s_addc_u32 s5, s51, 0
	s_add_u32 s6, s50, 0x4400
	s_addc_u32 s7, s51, 0
	v_readlane_b32 s8, v253, 0
	v_readlane_b32 s9, v253, 1
	s_waitcnt lgkmcnt(0)
	s_mul_i32 s2, s2, s8
	s_add_u32 s8, s50, 0x4500
	s_addc_u32 s9, s51, 0
	s_add_u32 s10, s50, 0x4600
	s_addc_u32 s11, s51, 0
	s_add_u32 s14, s50, 0x4700
	s_addc_u32 s15, s51, 0
	s_add_u32 s16, s50, 0x4800
	s_addc_u32 s17, s51, 0
	s_add_u32 s18, s50, 0x4900
	s_addc_u32 s19, s51, 0
	s_add_u32 s20, s50, 0x4a00
	s_addc_u32 s21, s51, 0
	s_add_u32 s22, s50, 0x4b00
	s_addc_u32 s23, s51, 0
	s_add_u32 s24, s50, 0x4c00
	s_addc_u32 s25, s51, 0
	s_add_u32 s26, s50, 0x4d00
	s_addc_u32 s27, s51, 0
	s_add_u32 s28, s50, 0x4e00
	s_addc_u32 s29, s51, 0
	s_add_u32 s30, s50, 0x4f00
	v_readlane_b32 s38, v253, 34
	s_addc_u32 s31, s51, 0
	v_readlane_b32 s39, v253, 35
	s_add_u32 s38, s50, 0x5000
	v_readlane_b32 s42, v253, 38
	s_addc_u32 s39, s51, 0
	v_readlane_b32 s43, v253, 39
	s_add_u32 s42, s50, 0x5100
	v_readlane_b32 s44, v253, 40
	s_addc_u32 s43, s51, 0
	v_readlane_b32 s45, v253, 41
	s_add_u32 s44, s50, 0x5200
	s_addc_u32 s45, s51, 0
	s_add_u32 s54, s50, 0x5300
	s_mul_i32 s2, s2, s3
	s_addc_u32 s55, s51, 0
	s_mov_b32 s3, 1
	v_mov_b32_e32 v18, 0
	v_readlane_b32 s37, v253, 33
	v_readlane_b32 s40, v253, 36
	v_readlane_b32 s41, v253, 37
	v_readlane_b32 s46, v253, 42
	v_readlane_b32 s47, v253, 43
	v_readlane_b32 s48, v253, 44
	v_readlane_b32 s49, v253, 45
	s_branch .LBB0_1365
